# v20: v18 + ret_scan K/V staging lanes permuted so ds_write_b128 into the transposed-read LDS layout is bank-conflict-free (K) or 2-way (V) instead of 4-way; LDS image unchanged
# speedup vs baseline: 1.0012x; 1.0012x over previous
; __device__ __forceinline__ float ret_log_gamma(const float* dexp, int dir, int h) { return log1pf(-exp2f(-dexp[dir * 8 + h])); }
; __device__ __forceinline__ void ret_scan(const bf16* proj, bf16* ST, bf16* FS, const float* dexp, LAS unsigned char* lds, int vb, int nb, int tid_in, int wave) {
;     ...
;         const int vs = c >> 5, h = (c >> 2) & 7, dir = (c >> 1) & 1, dsl = c & 1;
;         const bool seg = vs >= 8;
;         const int base = seg ? 16384 + (vs - 8) * 2048 : vs * 2048, N = 16, nsteps = seg ? 16 : 15;
;         const float lg = ret_log_gamma(dexp, dir, h), gC = expf(128.0f * lg);
;         f32x4 acc[8][2];
; #pragma unroll
;         for (int m = 0; m < 8; ++m) { acc[m][0] = (f32x4){0.f, 0.f, 0.f, 0.f}; acc[m][1] = (f32x4){0.f, 0.f, 0.f, 0.f}; }
;         v4u kr[4], vr[8];
;         { const int n0 = dir == 0 ? 0 : N - 1, rowb = base + n0 * 128;
; #pragma unroll
;           for (int i = 0; i < 4; ++i) { const int id = tid + 512 * i, j = id >> 4, ch = id & 15; kr[i] = *(const v4u*)(proj + (size_t)(rowb + j) * NIN + C_RK + h * 256 + dsl * 128 + ch * 8); }
; #pragma unroll
;           for (int i = 0; i < 8; ++i) { const int id = tid + 512 * i, j = id >> 5, ch = id & 31; vr[i] = *(const v4u*)(proj + (size_t)(rowb + j) * NIN + C_RV + h * 256 + ch * 8); } }
.LBB0_413:
	s_ashr_i32 s5, s46, 5
	s_bfe_u32 s47, s46, 0x30002
	s_bfe_i32 s42, s46, 0x10001
	s_bfe_u32 s4, s46, 0x10001
	s_cmp_gt_i32 s5, 7
	s_cselect_b32 s52, 16, 15
	s_lshl_b32 s30, s47, 2
	s_lshl_b32 s31, s4, 5
	s_or_b32 s30, s31, s30
	v_mov_b32_e32 v102, v146
	v_bfe_u32 v248, v146, 1, 2
	v_bfe_u32 v250, v146, 3, 3
	v_lshlrev_b32_e32 v248, 4, v248
	v_lshl_or_b32 v248, v250, 1, v248
	v_and_b32_e32 v250, 0x1c1, v146
	v_or_b32_e32 v248, v248, v250
	v_bfe_u32 v249, v146, 1, 1
	v_lshlrev_b32_e32 v249, 5, v249
	v_or_b32_e32 v249, v249, v250
	v_bfe_u32 v250, v146, 2, 4
	v_lshl_or_b32 v249, v250, 1, v249
	v_mov_b32_e32 v1, s30
	global_load_dword v2, v1, s[16:17]
	s_mov_b32 s30, 0x42fc0000
	s_waitcnt vmcnt(12)
	v_lshlrev_b32_e32 v3, 3, v102
	v_and_b32_e32 v114, 0x78, v3
	v_lshlrev_b32_e32 v116, 3, v249
	v_and_b32_e32 v116, 0xf8, v116
	v_ashrrev_i32_e32 v1, 4, v248
	v_add_u32_e32 v65, 0xe00, v249
	v_ashrrev_i32_e32 v181, 5, v65
	v_add_u32_e32 v64, 0xc00, v249
	s_waitcnt vmcnt(2)
	v_mov_b64_e32 v[42:43], s[6:7]
	v_ashrrev_i32_e32 v180, 5, v64
	v_add_u32_e32 v63, 0xa00, v249
	v_lshlrev_b32_e32 v182, 1, v116
	v_add_u32_e32 v19, 0x200, v249
	v_ashrrev_i32_e32 v179, 5, v63
	v_add_u32_e32 v147, 32, v1
	v_add_u32_e32 v62, 0x800, v249
	v_ashrrev_i32_e32 v178, 5, v62
	v_add_u32_e32 v17, 0x600, v249
	v_ashrrev_i32_e32 v175, 5, v19
	v_ashrrev_i32_e32 v177, 5, v17
	v_add_u32_e32 v18, 0x400, v249
	v_ashrrev_i32_e32 v176, 5, v18
	v_add_u32_e32 v173, 0x60, v1
	v_add_u32_e32 v172, 64, v1
	v_ashrrev_i32_e32 v174, 5, v249
	s_movk_i32 s59, 0x440
	v_bfe_u32 v110, v102, 4, 2
	v_add_u32_e32 v115, s44, v114
	v_add_u32_e32 v117, 0, v114
	v_lshl_or_b32 v111, v110, 1, 8
	v_mad_u32_u24 v103, v111, s59, v117
	v_and_b32_e32 v149, 15, v102
	v_mul_u32_u24_e32 v210, 0x1080, v110
	s_waitcnt vmcnt(0)
	v_cmp_lt_f32_e32 vcc, s30, v2
	s_nop 1
	v_cndmask_b32_e32 v3, 0, v219, vcc
	s_and_b64 s[30:31], vcc, exec
	v_sub_f32_e32 v2, v3, v2
	s_cselect_b32 s36, 0xffffffc0, 0
	s_lshl_b32 s53, s5, 11
	s_lshl_b32 s5, s5, 3
	v_exp_f32_e32 v2, v2
	s_lshl_b32 s30, s46, 7
	s_or_b32 s5, s5, s47
	s_and_b32 s64, s30, 0x80
	s_sub_i32 s30, s5, 64
	s_ashr_i32 s31, s30, 31
	s_lshl_b32 s43, s47, 8
	s_lshl_b64 s[30:31], s[30:31], 18
	v_ldexp_f32 v16, v2, s36
	s_add_u32 s5, s28, s30
	v_sub_f32_e32 v4, 1.0, v16
	s_addc_u32 s30, s29, s31
	s_lshl_b32 s31, s4, 17
	v_add_f32_e32 v5, -1.0, v4
	v_frexp_mant_f32_e32 v6, v4
	v_cvt_f64_f32_e32 v[2:3], v4
	s_add_u32 s54, s5, s31
	s_mov_b32 s5, 0x3f2aaaab
	v_sub_f32_e32 v7, v5, v4
	v_frexp_exp_i32_f64_e32 v2, v[2:3]
	v_cmp_gt_f32_e32 vcc, s5, v6
	v_sub_f32_e64 v5, -v16, v5
	v_add_f32_e32 v3, 1.0, v7
	v_subbrev_co_u32_e32 v2, vcc, 0, v2, vcc
	v_add_f32_e32 v3, v5, v3
	v_sub_u32_e32 v5, 0, v2
	v_ldexp_f32 v4, v4, v5
	v_add_f32_e32 v6, -1.0, v4
	v_add_f32_e32 v7, 1.0, v4
	v_ldexp_f32 v3, v3, v5
	v_add_f32_e32 v5, 1.0, v6
	v_add_f32_e32 v8, -1.0, v7
	v_sub_f32_e32 v5, v4, v5
	v_sub_f32_e32 v4, v4, v8
	v_add_f32_e32 v8, v3, v5
	v_add_f32_e32 v3, v3, v4
	v_add_f32_e32 v10, v7, v3
	v_rcp_f32_e32 v11, v10
	v_add_f32_e32 v5, v6, v8
	v_sub_f32_e32 v6, v5, v6
	v_sub_f32_e32 v4, v10, v7
	v_mul_f32_e32 v13, v5, v11
	v_sub_f32_e32 v12, v8, v6
	v_mul_f32_e32 v6, v10, v13
	v_sub_f32_e32 v3, v3, v4
	v_fma_f32 v8, v13, v10, -v6
	v_fmac_f32_e32 v8, v13, v3
	v_add_f32_e32 v4, v6, v8
	v_sub_f32_e32 v7, v5, v4
	v_mov_b32_e32 v9, v4
	v_pk_add_f32 v[4:5], v[4:5], v[6:7] neg_lo:[0,1] neg_hi:[0,1]
	v_cvt_f32_i32_e32 v2, v2
	v_pk_add_f32 v[4:5], v[4:5], v[8:9] neg_lo:[0,1] neg_hi:[0,1]
	s_addc_u32 s55, s30, 0
	v_add_f32_e32 v5, v12, v5
	v_add_f32_e32 v4, v4, v5
	v_add_f32_e32 v5, v7, v4
	v_mul_f32_e32 v9, v11, v5
	v_mul_f32_e32 v6, v10, v9
	v_sub_f32_e32 v7, v7, v5
	v_add_f32_e32 v14, v13, v9
	v_fma_f32 v8, v9, v10, -v6
	v_add_f32_e32 v12, v4, v7
	v_sub_f32_e32 v4, v14, v13
	v_fmac_f32_e32 v8, v9, v3
	v_sub_f32_e32 v3, v9, v4
	v_add_f32_e32 v4, v6, v8
	v_sub_f32_e32 v7, v5, v4
	v_mov_b32_e32 v9, v4
	v_pk_add_f32 v[4:5], v[4:5], v[6:7] neg_lo:[0,1] neg_hi:[0,1]
	s_ashr_i32 s36, s53, 7
	v_pk_add_f32 v[4:5], v[4:5], v[8:9] neg_lo:[0,1] neg_hi:[0,1]
	s_cmp_eq_u32 s4, 0
	v_add_f32_e32 v5, v12, v5
	v_add_f32_e32 v4, v4, v5
	v_add_f32_e32 v4, v7, v4
	v_mul_f32_e32 v4, v11, v4
	v_add_f32_e32 v3, v3, v4
	v_add_f32_e32 v4, v14, v3
	v_mul_f32_e32 v6, v4, v4
	v_sub_f32_e32 v7, v4, v14
	v_fmamk_f32 v8, v6, 0x3e9b6dac, v213
	v_sub_f32_e32 v7, v3, v7
	v_mul_f32_e32 v3, v4, v6
	v_fmaak_f32 v185, v6, v8, 0x3f2aaada
	v_ldexp_f32 v9, v7, 1
	v_pk_mul_f32 v[6:7], v[2:3], v[184:185]
	s_mov_b32 s4, 0x3f317218
	v_ldexp_f32 v5, v4, 1
	v_fma_f32 v4, v2, s4, -v6
	v_fmac_f32_e32 v4, 0xb102e308, v2
	v_pk_add_f32 v[2:3], v[6:7], v[4:5]
	v_mov_b32_e32 v8, v6
	v_sub_f32_e32 v12, v3, v5
	v_pk_add_f32 v[10:11], v[2:3], v[6:7] neg_lo:[0,1] neg_hi:[0,1]
	v_sub_f32_e32 v7, v7, v12
	v_add_f32_e32 v9, v9, v7
	v_pk_add_f32 v[14:15], v[2:3], v[8:9]
	v_mov_b32_e32 v5, v2
	v_mov_b32_e32 v11, v15
	v_pk_add_f32 v[20:21], v[4:5], v[10:11] neg_lo:[0,1] neg_hi:[0,1]
	v_pk_add_f32 v[4:5], v[4:5], v[10:11]
	v_mov_b32_e32 v6, v3
	v_mov_b32_e32 v13, v2
	v_pk_add_f32 v[2:3], v[4:5], v[2:3] op_sel:[1,0] op_sel_hi:[0,1] neg_lo:[0,1] neg_hi:[0,1]
	v_mov_b32_e32 v12, v9
	v_mov_b32_e32 v8, v15
	v_mov_b32_e32 v9, v5
	v_mov_b32_e32 v7, v2
	v_pk_add_f32 v[10:11], v[14:15], v[2:3] op_sel_hi:[1,0] neg_lo:[0,1] neg_hi:[0,1]
	v_pk_add_f32 v[2:3], v[8:9], v[6:7] neg_lo:[0,1] neg_hi:[0,1]
	v_mov_b32_e32 v10, v20
	v_pk_add_f32 v[2:3], v[12:13], v[2:3] neg_lo:[0,1] neg_hi:[0,1]
	v_mov_b32_e32 v21, v5
	v_pk_add_f32 v[6:7], v[10:11], v[2:3]
	v_cmp_nlt_f32_e32 vcc, 1.0, v16
	v_pk_add_f32 v[8:9], v[6:7], v[6:7] op_sel:[0,1] op_sel_hi:[1,0]
	s_mov_b32 s4, 0x33800000
; __device__ __forceinline__ float ret_log_gamma(const float* dexp, int dir, int h) { return log1pf(-exp2f(-dexp[dir * 8 + h])); }
; __device__ __forceinline__ void ret_scan(const bf16* proj, bf16* ST, bf16* FS, const float* dexp, LAS unsigned char* lds, int vb, int nb, int tid_in, int wave) {
;     ...
;         const float lg = ret_log_gamma(dexp, dir, h), gC = expf(128.0f * lg);
;         f32x4 acc[8][2];
; #pragma unroll
;         for (int m = 0; m < 8; ++m) { acc[m][0] = (f32x4){0.f, 0.f, 0.f, 0.f}; acc[m][1] = (f32x4){0.f, 0.f, 0.f, 0.f}; }
;         v4u kr[4], vr[8];
;         { const int n0 = dir == 0 ? 0 : N - 1, rowb = base + n0 * 128;
; #pragma unroll
;           for (int i = 0; i < 4; ++i) { const int id = tid + 512 * i, j = id >> 4, ch = id & 15; kr[i] = *(const v4u*)(proj + (size_t)(rowb + j) * NIN + C_RK + h * 256 + dsl * 128 + ch * 8); }
; #pragma unroll
;           for (int i = 0; i < 8; ++i) { const int id = tid + 512 * i, j = id >> 5, ch = id & 31; vr[i] = *(const v4u*)(proj + (size_t)(rowb + j) * NIN + C_RV + h * 256 + ch * 8); } }
	v_pk_add_f32 v[4:5], v[4:5], v[8:9] op_sel:[1,0] op_sel_hi:[0,1]
	v_mov_b32_e32 v7, v4
	v_mov_b32_e32 v3, v8
	v_pk_add_f32 v[8:9], v[6:7], v[20:21] neg_lo:[0,1] neg_hi:[0,1]
	v_cmp_lt_f32_e64 s[4:5], |v16|, s4
	v_sub_f32_e32 v5, v6, v8
	v_pk_add_f32 v[2:3], v[2:3], v[8:9] neg_lo:[0,1] neg_hi:[0,1]
	v_sub_f32_e32 v5, v20, v5
	v_add_f32_e32 v2, v2, v5
	v_add_f32_e32 v2, v2, v3
	v_add_f32_e32 v2, v4, v2
	v_cndmask_b32_e32 v2, v220, v2, vcc
	v_cmp_neq_f32_e32 vcc, 1.0, v16
	s_movk_i32 s30, 0x700
	v_and_b32_e32 v14, 15, v248
	v_lshlrev_b32_e32 v14, 4, v14
	v_cndmask_b32_e32 v2, v221, v2, vcc
	v_cndmask_b32_e64 v20, v2, -v16, s[4:5]
	v_mul_f32_e32 v2, 0x43000000, v20
	v_mul_f32_e32 v3, 0x3fb8aa3b, v2
	v_fma_f32 v4, v2, s96, -v3
	v_rndne_f32_e32 v5, v3
	v_fmac_f32_e32 v4, 0x32a5705f, v2
	v_sub_f32_e32 v3, v3, v5
	v_add_f32_e32 v3, v3, v4
	v_exp_f32_e32 v3, v3
	v_cvt_i32_f32_e32 v4, v5
	v_cmp_ngt_f32_e32 vcc, s97, v2
	s_cselect_b64 s[4:5], -1, 0
	s_and_b64 s[50:51], s[4:5], exec
	v_ldexp_f32 v3, v3, v4
	v_cndmask_b32_e32 v3, 0, v3, vcc
	v_cmp_nlt_f32_e32 vcc, s12, v2
	v_sub_u32_e32 v2, 0x7f, v1
	v_cndmask_b32_e64 v21, v1, v2, s[4:5]
	s_cselect_b32 s56, 1, -1
	v_lshlrev_b32_e32 v2, 1, v248
	v_and_b32_e32 v66, 28, v2
	v_lshlrev_b32_e32 v2, 4, v102
	s_cselect_b32 s30, 0x80, s30
	s_add_i32 s56, s56, s36
	v_and_b32_e32 v2, 16, v2
	s_add_u32 s57, s26, s31
	v_add_u32_e32 v16, 0, v2
	v_lshlrev_b32_e32 v2, 6, v249
	s_addc_u32 s58, s27, 0
	s_and_b32 s31, s42, 0x780
	v_cndmask_b32_e32 v148, v222, v3, vcc
	v_and_b32_e32 v2, 0x780, v2
	v_and_b32_e32 v3, 0x60, v249
	s_or_b32 s31, s31, s53
	v_add3_u32 v67, v16, v2, v3
	v_add_u32_e32 v2, s31, v181
	v_mad_i64_i32 v[2:3], s[36:37], v2, s33, v[42:43]
	s_lshl_b32 s62, s47, 9
	v_lshl_add_u64 v[2:3], v[2:3], 0, s[62:63]
	v_add_u32_e32 v4, s31, v180
	v_lshl_add_u64 v[2:3], v[2:3], 0, v[182:183]
	v_mad_i64_i32 v[4:5], s[36:37], v4, s33, v[42:43]
	v_add_co_u32_e32 v2, vcc, s40, v2
	v_lshl_add_u64 v[4:5], v[4:5], 0, s[62:63]
	v_add_u32_e32 v10, s31, v179
	v_addc_co_u32_e32 v3, vcc, 0, v3, vcc
	v_lshl_add_u64 v[4:5], v[4:5], 0, v[182:183]
	v_mad_i64_i32 v[10:11], s[36:37], v10, s33, v[42:43]
	v_add_u32_e32 v12, s31, v147
	v_add_co_u32_e32 v6, vcc, s40, v4
	v_lshl_add_u64 v[10:11], v[10:11], 0, s[62:63]
	v_mad_i64_i32 v[12:13], s[50:51], v12, s33, v[42:43]
	v_addc_co_u32_e32 v7, vcc, 0, v5, vcc
	v_lshl_add_u64 v[10:11], v[10:11], 0, v[182:183]
	s_lshl_b32 s36, s64, 1
	s_mov_b32 s37, s63
	v_lshl_add_u64 v[12:13], v[12:13], 0, s[62:63]
	v_add_u32_e32 v22, s31, v1
	v_add_co_u32_e32 v10, vcc, s40, v10
	v_mov_b32_e32 v15, v183
	v_lshl_add_u64 v[12:13], v[12:13], 0, s[36:37]
	v_mad_i64_i32 v[22:23], s[50:51], v22, s33, v[42:43]
	v_addc_co_u32_e32 v11, vcc, 0, v11, vcc
	v_lshl_add_u64 v[12:13], v[12:13], 0, v[14:15]
	v_lshl_add_u64 v[22:23], v[22:23], 0, s[62:63]
	v_add_co_u32_e32 v12, vcc, s49, v12
	v_lshl_add_u64 v[22:23], v[22:23], 0, s[36:37]
	s_nop 0
	v_addc_co_u32_e32 v13, vcc, 0, v13, vcc
	v_lshl_add_u64 v[22:23], v[22:23], 0, v[14:15]
	v_add_co_u32_e32 v26, vcc, s49, v22
	global_load_dwordx4 v[2:5], v[2:3], off
	s_nop 0
	global_load_dwordx4 v[6:9], v[6:7], off
	v_addc_co_u32_e32 v27, vcc, 0, v23, vcc
	global_load_dwordx4 v[22:25], v[12:13], off
	s_nop 0
	global_load_dwordx4 v[26:29], v[26:27], off
	v_add_u32_e32 v30, s31, v178
	v_mad_i64_i32 v[12:13], s[50:51], v30, s33, v[42:43]
	v_lshl_add_u64 v[12:13], v[12:13], 0, s[62:63]
	v_add_u32_e32 v34, s31, v177
	v_add_u32_e32 v44, s31, v175
	v_lshl_add_u64 v[12:13], v[12:13], 0, v[182:183]
	v_mad_i64_i32 v[34:35], s[50:51], v34, s33, v[42:43]
	v_mad_i64_i32 v[44:45], s[50:51], v44, s33, v[42:43]
	v_add_co_u32_e32 v30, vcc, s40, v12
	v_lshl_add_u64 v[34:35], v[34:35], 0, s[62:63]
	v_add_u32_e32 v36, s31, v176
	v_lshl_add_u64 v[44:45], v[44:45], 0, s[62:63]
	v_addc_co_u32_e32 v31, vcc, 0, v13, vcc
	v_lshl_add_u64 v[34:35], v[34:35], 0, v[182:183]
	v_mad_i64_i32 v[36:37], s[50:51], v36, s33, v[42:43]
	v_lshl_add_u64 v[52:53], v[44:45], 0, v[182:183]
	v_add_u32_e32 v44, s31, v173
	v_add_co_u32_e32 v34, vcc, s40, v34
	v_lshl_add_u64 v[36:37], v[36:37], 0, s[62:63]
	v_mad_i64_i32 v[44:45], s[50:51], v44, s33, v[42:43]
	v_addc_co_u32_e32 v35, vcc, 0, v35, vcc
	v_lshl_add_u64 v[36:37], v[36:37], 0, v[182:183]
	v_lshl_add_u64 v[44:45], v[44:45], 0, s[62:63]
	v_add_u32_e32 v46, s31, v172
	v_add_co_u32_e32 v38, vcc, s40, v36
	v_lshl_add_u64 v[44:45], v[44:45], 0, s[36:37]
	v_mad_i64_i32 v[46:47], s[50:51], v46, s33, v[42:43]
	v_addc_co_u32_e32 v39, vcc, 0, v37, vcc
	v_lshl_add_u64 v[44:45], v[44:45], 0, v[14:15]
	v_lshl_add_u64 v[46:47], v[46:47], 0, s[62:63]
	v_add_co_u32_e32 v44, vcc, s49, v44
	v_lshl_add_u64 v[46:47], v[46:47], 0, s[36:37]
	s_nop 0
	v_addc_co_u32_e32 v45, vcc, 0, v45, vcc
	v_lshl_add_u64 v[46:47], v[46:47], 0, v[14:15]
	v_add_co_u32_e32 v48, vcc, s49, v46
	global_load_dwordx4 v[10:13], v[10:11], off
	s_nop 0
	global_load_dwordx4 v[30:33], v[30:31], off
	v_addc_co_u32_e32 v49, vcc, 0, v47, vcc
	global_load_dwordx4 v[34:37], v[34:35], off
	s_nop 0
	global_load_dwordx4 v[38:41], v[38:39], off
	s_nop 0
	global_load_dwordx4 v[44:47], v[44:45], off
	s_nop 0
	global_load_dwordx4 v[48:51], v[48:49], off
	v_cvt_f32_i32_e32 v21, v21
	v_add_u32_e32 v54, s31, v174
	v_mad_i64_i32 v[54:55], s[50:51], v54, s33, v[42:43]
	v_add_co_u32_e32 v52, vcc, s40, v52
	v_lshl_add_u64 v[54:55], v[54:55], 0, s[62:63]
	s_nop 0
	v_addc_co_u32_e32 v53, vcc, 0, v53, vcc
	v_lshl_add_u64 v[54:55], v[54:55], 0, v[182:183]
	v_mul_f32_e32 v21, v20, v21
	v_add_co_u32_e32 v56, vcc, s40, v54
	v_mul_f32_e32 v21, 0x3fb8aa3b, v21
	s_nop 0
	v_addc_co_u32_e32 v57, vcc, 0, v55, vcc
	v_exp_f32_e32 v150, v21
	global_load_dwordx4 v[52:55], v[52:53], off
	s_nop 0
	global_load_dwordx4 v[56:59], v[56:57], off
	v_lshrrev_b32_e32 v21, 6, v102
	v_mov_b32_e32 v151, v150
	s_barrier
; #define LAS __attribute__((address_space(3)))
; __device__ __forceinline__ unsigned pk2(float lo, float hi) { const f32x2 v = {lo, hi}; return __builtin_bit_cast(unsigned, __builtin_convertvector(v, bf16x2_t)); }
; __device__ __forceinline__ int trw_off(int row, int c8  , int GP) { return (row >> 2) * GP + (((c8 >> 1) * 4 + (row & 3)) * 32) + (c8 & 1) * 16; }
; __device__ __forceinline__ void ret_scan(const bf16* proj, bf16* ST, bf16* FS, const float* dexp, LAS unsigned char* lds, int vb, int nb, int tid_in, int wave) {
;     ...
;                 __syncthreads();
; #pragma unroll
;                 for (int i = 0; i < 4; ++i) { const int id = tid + 512 * i, j = id >> 4, ch = id & 15;
;                     v4u val = kr[i];
;                     const float z = __expf(lg * (float)(dir == 0 ? 127 - j : j));
;                     val.x = pk2(bflo(val.x) * z, bfhi(val.x) * z); val.y = pk2(bflo(val.y) * z, bfhi(val.y) * z); val.z = pk2(bflo(val.z) * z, bfhi(val.z) * z); val.w = pk2(bflo(val.w) * z, bfhi(val.w) * z);
;                     *(LAS v4u*)(Kt + trw_off(j, ch, 1088)) = val; }
; #pragma unroll
;                 for (int i = 0; i < 8; ++i) { const int id = tid + 512 * i, j = id >> 5, ch = id & 31; *(LAS v4u*)(Vt + trw_off(j, ch, 2112)) = vr[i]; }
;                 __syncthreads();
	s_movk_i32 s31, 0x1080
	s_waitcnt vmcnt(8)
	v_lshlrev_b32_e32 v60, 16, v26
	v_and_b32_e32 v61, 0xffff0000, v26
	v_pk_mul_f32 v[60:61], v[150:151], v[60:61] op_sel_hi:[0,1]
	v_cvt_pk_bf16_f32 v26, v60, v61
	v_lshlrev_b32_e32 v60, 16, v27
	v_and_b32_e32 v61, 0xffff0000, v27
	v_pk_mul_f32 v[60:61], v[150:151], v[60:61] op_sel_hi:[0,1]
	v_cvt_pk_bf16_f32 v27, v60, v61
	v_lshlrev_b32_e32 v60, 16, v28
	v_and_b32_e32 v61, 0xffff0000, v28
	v_pk_mul_f32 v[60:61], v[150:151], v[60:61] op_sel_hi:[0,1]
	v_cvt_pk_bf16_f32 v28, v60, v61
	v_lshlrev_b32_e32 v60, 16, v29
	v_and_b32_e32 v61, 0xffff0000, v29
	v_pk_mul_f32 v[60:61], v[150:151], v[60:61] op_sel_hi:[0,1]
	v_cvt_pk_bf16_f32 v29, v60, v61
	v_and_or_b32 v60, v1, 3, v66
	v_lshlrev_b32_e32 v68, 5, v60
	v_sub_u32_e32 v60, 0x7f, v147
	v_cndmask_b32_e64 v60, v147, v60, s[4:5]
	v_cvt_f32_i32_e32 v69, v60
	v_mad_u64_u32 v[60:61], s[50:51], v21, s59, v[16:17]
	v_add_u32_e32 v185, v60, v68
	v_mul_f32_e32 v21, v20, v69
	v_mul_f32_e32 v21, 0x3fb8aa3b, v21
	v_exp_f32_e32 v152, v21
	ds_write_b128 v185, v[26:29]
	v_lshlrev_b32_e32 v26, 16, v22
	v_and_b32_e32 v27, 0xffff0000, v22
	v_mov_b32_e32 v153, v152
	v_pk_mul_f32 v[26:27], v[152:153], v[26:27] op_sel_hi:[0,1]
	v_cvt_pk_bf16_f32 v22, v26, v27
	v_lshlrev_b32_e32 v26, 16, v23
	v_and_b32_e32 v27, 0xffff0000, v23
	v_pk_mul_f32 v[26:27], v[152:153], v[26:27] op_sel_hi:[0,1]
	v_cvt_pk_bf16_f32 v23, v26, v27
	v_lshlrev_b32_e32 v26, 16, v24
	v_and_b32_e32 v27, 0xffff0000, v24
	v_pk_mul_f32 v[26:27], v[152:153], v[26:27] op_sel_hi:[0,1]
	v_cvt_pk_bf16_f32 v24, v26, v27
	v_lshlrev_b32_e32 v26, 16, v25
	v_and_b32_e32 v27, 0xffff0000, v25
	v_pk_mul_f32 v[26:27], v[152:153], v[26:27] op_sel_hi:[0,1]
	v_cvt_pk_bf16_f32 v25, v26, v27
	v_and_or_b32 v26, v147, 3, v66
	v_lshlrev_b32_e32 v28, 5, v26
	v_sub_u32_e32 v26, 0x7f, v172
	v_cndmask_b32_e64 v26, v172, v26, s[4:5]
	v_cvt_f32_i32_e32 v29, v26
	v_lshrrev_b32_e32 v21, 6, v19
	v_mad_u64_u32 v[26:27], s[50:51], v21, s59, v[16:17]
	v_mul_f32_e32 v21, v20, v29
	v_mul_f32_e32 v21, 0x3fb8aa3b, v21
	v_exp_f32_e32 v154, v21
	v_add_u32_e32 v186, v26, v28
	ds_write_b128 v186, v[22:25]
	s_waitcnt vmcnt(2)
	v_lshlrev_b32_e32 v22, 16, v48
	v_and_b32_e32 v23, 0xffff0000, v48
	v_mov_b32_e32 v155, v154
	v_lshlrev_b32_e32 v24, 16, v49
	v_and_b32_e32 v25, 0xffff0000, v49
	v_pk_mul_f32 v[22:23], v[154:155], v[22:23] op_sel_hi:[0,1]
	v_pk_mul_f32 v[24:25], v[154:155], v[24:25] op_sel_hi:[0,1]
	v_cvt_pk_bf16_f32 v22, v22, v23
	v_cvt_pk_bf16_f32 v23, v24, v25
	v_lshlrev_b32_e32 v24, 16, v50
	v_and_b32_e32 v25, 0xffff0000, v50
	v_lshlrev_b32_e32 v26, 16, v51
	v_and_b32_e32 v27, 0xffff0000, v51
	v_pk_mul_f32 v[24:25], v[154:155], v[24:25] op_sel_hi:[0,1]
	v_pk_mul_f32 v[26:27], v[154:155], v[26:27] op_sel_hi:[0,1]
	v_cvt_pk_bf16_f32 v24, v24, v25
	v_cvt_pk_bf16_f32 v25, v26, v27
	v_and_or_b32 v26, v172, 3, v66
	v_lshlrev_b32_e32 v28, 5, v26
	v_sub_u32_e32 v26, 0x7f, v173
	v_cndmask_b32_e64 v26, v173, v26, s[4:5]
	v_cvt_f32_i32_e32 v29, v26
	v_lshrrev_b32_e32 v21, 6, v18
	v_mad_u64_u32 v[26:27], s[50:51], v21, s59, v[16:17]
	v_mul_f32_e32 v20, v20, v29
	v_mul_f32_e32 v20, 0x3fb8aa3b, v20
	v_exp_f32_e32 v156, v20
	v_add_u32_e32 v189, v26, v28
	ds_write_b128 v189, v[22:25]
	v_lshlrev_b32_e32 v20, 16, v44
	v_and_b32_e32 v21, 0xffff0000, v44
	v_mov_b32_e32 v157, v156
	v_lshlrev_b32_e32 v22, 16, v45
	v_and_b32_e32 v23, 0xffff0000, v45
	v_pk_mul_f32 v[20:21], v[156:157], v[20:21] op_sel_hi:[0,1]
	v_pk_mul_f32 v[22:23], v[156:157], v[22:23] op_sel_hi:[0,1]
	v_cvt_pk_bf16_f32 v20, v20, v21
	v_cvt_pk_bf16_f32 v21, v22, v23
	v_lshlrev_b32_e32 v22, 16, v46
	v_and_b32_e32 v23, 0xffff0000, v46
	v_lshlrev_b32_e32 v24, 16, v47
	v_and_b32_e32 v25, 0xffff0000, v47
	v_pk_mul_f32 v[22:23], v[156:157], v[22:23] op_sel_hi:[0,1]
	v_pk_mul_f32 v[24:25], v[156:157], v[24:25] op_sel_hi:[0,1]
	v_cvt_pk_bf16_f32 v22, v22, v23
	v_cvt_pk_bf16_f32 v23, v24, v25
	v_lshrrev_b32_e32 v24, 6, v17
	v_and_or_b32 v25, v173, 3, v66
	v_lshlrev_b32_e32 v26, 5, v25
	v_mad_u64_u32 v[24:25], s[50:51], v24, s59, v[16:17]
	v_ashrrev_i32_e32 v16, 7, v102
	v_mul_lo_u32 v16, v16, s73
	v_add_u32_e32 v192, v67, v16
	v_ashrrev_i32_e32 v16, 7, v19
	v_mul_lo_u32 v16, v16, s73
	v_add_u32_e32 v198, v67, v16
	v_ashrrev_i32_e32 v16, 7, v18
	v_mul_lo_u32 v16, v16, s73
	v_add_u32_e32 v199, v67, v16
	v_ashrrev_i32_e32 v16, 7, v17
	v_mul_lo_u32 v16, v16, s73
	v_add_u32_e32 v200, v67, v16
	v_ashrrev_i32_e32 v16, 7, v62
	v_mul_lo_u32 v16, v16, s73
	v_add_u32_e32 v201, v67, v16
	v_ashrrev_i32_e32 v16, 7, v63
	v_mul_lo_u32 v16, v16, s73
	v_add_u32_e32 v190, v24, v26
	v_add_u32_e32 v202, v67, v16
	ds_write_b128 v190, v[20:23]
	s_waitcnt vmcnt(0)
	ds_write_b128 v192, v[56:59] offset:34816
	ds_write_b128 v198, v[52:55] offset:34816
	ds_write_b128 v199, v[38:41] offset:34816
	ds_write_b128 v200, v[34:37] offset:34816
	ds_write_b128 v201, v[30:33] offset:34816
	ds_write_b128 v202, v[10:13] offset:34816
	v_ashrrev_i32_e32 v10, 7, v64
	v_mul_lo_u32 v10, v10, s73
	v_add_u32_e32 v203, v67, v10
	ds_write_b128 v203, v[6:9] offset:34816
	v_ashrrev_i32_e32 v6, 7, v65
	v_mul_lo_u32 v6, v6, s73
	v_add_u32_e32 v204, v67, v6
	v_mad_u32_u24 v16, v110, s31, v115
	v_mad_u32_u24 v40, v110, s77, v117
	ds_write_b128 v204, v[2:5] offset:34816
	s_waitcnt lgkmcnt(0)
	s_barrier
; #define LAS __attribute__((address_space(3)))
; __device__ __forceinline__ s16x4 tr16(const LAS unsigned char* p) { return __builtin_bit_cast(s16x4, __builtin_amdgcn_ds_read_tr16_b64_v4i16((LAS s16x4*)p)); }
; __device__ __forceinline__ bf16x8 cat8(s16x4 lo, s16x4 hi) { return __builtin_shufflevector(lo, hi, 0, 1, 2, 3, 4, 5, 6, 7); }
; __device__ __forceinline__ f32x4 mfma16(bf16x8 a, bf16x8 b, f32x4 c) { return __builtin_amdgcn_mfma_f32_16x16x32_bf16(a, b, c, 0, 0, 0); }
; __device__ __forceinline__ void ret_scan(const bf16* proj, bf16* ST, bf16* FS, const float* dexp, LAS unsigned char* lds, int vb, int nb, int tid_in, int wave) {
;     ...
;             for (int m = 0; m < 8; ++m) { acc[m][0] = acc[m][0] * gC; acc[m][1] = acc[m][1] * gC; }
; #pragma unroll
;             for (int ks = 0; ks < 4; ++ks) {
;                 const int rho = 8 * ks + 2 * g, lo8 = (qi >> 2) * 32 + (qi & 3) * 8;
;                 bf16x8 bfr[2];
; #pragma unroll
;                 for (int nt = 0; nt < 2; ++nt) { const LAS unsigned char* p = Vt + rho * 2112 + (2 * wave + nt) * 128 + lo8; bfr[nt] = cat8(tr16(p), tr16(p + 2112)); }
; #pragma unroll
;                 for (int m = 0; m < 8; ++m) { const LAS unsigned char* p = Kt + rho * 1088 + m * 128 + lo8; const bf16x8 af = cat8(tr16(p), tr16(p + 1088));
;                     acc[m][0] = mfma16(af, bfr[0], acc[m][0]); acc[m][1] = mfma16(af, bfr[1], acc[m][1]); }
	v_mul_f32_e32 v2, 0, v148
	ds_read_b64_tr_b16 v[6:7], v40
	ds_read_b64_tr_b16 v[8:9], v40 offset:1088
	ds_read_b64_tr_b16 v[10:11], v16 offset:34816
	ds_read_b64_tr_b16 v[12:13], v16 offset:36928
	ds_read_b64_tr_b16 v[18:19], v16 offset:37056
	ds_read_b64_tr_b16 v[16:17], v16 offset:34944
	ds_read_b64_tr_b16 v[20:21], v40 offset:128
	ds_read_b64_tr_b16 v[24:25], v40 offset:256
	ds_read_b64_tr_b16 v[28:29], v40 offset:384
	ds_read_b64_tr_b16 v[22:23], v40 offset:1216
	ds_read_b64_tr_b16 v[26:27], v40 offset:1344
	ds_read_b64_tr_b16 v[30:31], v40 offset:1472
	ds_read_b64_tr_b16 v[52:53], v40 offset:512
	ds_read_b64_tr_b16 v[54:55], v40 offset:1600
	ds_read_b64_tr_b16 v[56:57], v40 offset:640
	ds_read_b64_tr_b16 v[60:61], v40 offset:768
	ds_read_b64_tr_b16 v[64:65], v40 offset:896
	ds_read_b64_tr_b16 v[58:59], v40 offset:1728
	ds_read_b64_tr_b16 v[62:63], v40 offset:1856
	ds_read_b64_tr_b16 v[66:67], v40 offset:1984
	v_mov_b32_e32 v3, v2
	v_mov_b32_e32 v4, v2
	v_mov_b32_e32 v5, v2
	v_mad_u32_u24 v40, v111, s73, v115
	s_or_b32 s30, s30, s53
	s_waitcnt lgkmcnt(14)
	v_mfma_f32_16x16x32_bf16 v[32:35], v[6:9], v[10:13], v[2:5]
	s_mov_b32 s59, 1
	v_mov_b32_e32 v158, v148
	v_mov_b32_e32 v159, v148
	v_mfma_f32_16x16x32_bf16 v[6:9], v[6:9], v[16:19], v[2:5]
	s_waitcnt lgkmcnt(10)
	v_mfma_f32_16x16x32_bf16 v[36:39], v[20:23], v[10:13], v[2:5]
	v_mfma_f32_16x16x32_bf16 v[20:23], v[20:23], v[16:19], v[2:5]
	s_waitcnt lgkmcnt(9)
	v_mfma_f32_16x16x32_bf16 v[44:47], v[24:27], v[10:13], v[2:5]
	v_mfma_f32_16x16x32_bf16 v[24:27], v[24:27], v[16:19], v[2:5]
	s_waitcnt lgkmcnt(8)
	v_mfma_f32_16x16x32_bf16 v[48:51], v[28:31], v[10:13], v[2:5]
	v_mfma_f32_16x16x32_bf16 v[28:31], v[28:31], v[16:19], v[2:5]
	s_waitcnt lgkmcnt(6)
	v_mfma_f32_16x16x32_bf16 v[68:71], v[52:55], v[10:13], v[2:5]
	v_mfma_f32_16x16x32_bf16 v[52:55], v[52:55], v[16:19], v[2:5]
	s_waitcnt lgkmcnt(2)
	v_mfma_f32_16x16x32_bf16 v[72:75], v[56:59], v[10:13], v[2:5]
	v_mfma_f32_16x16x32_bf16 v[56:59], v[56:59], v[16:19], v[2:5]
	s_waitcnt lgkmcnt(1)
	v_mfma_f32_16x16x32_bf16 v[76:79], v[60:63], v[10:13], v[2:5]
	v_mfma_f32_16x16x32_bf16 v[60:63], v[60:63], v[16:19], v[2:5]
	s_waitcnt lgkmcnt(0)
	v_mfma_f32_16x16x32_bf16 v[10:13], v[64:67], v[10:13], v[2:5]
	v_mfma_f32_16x16x32_bf16 v[16:19], v[64:67], v[16:19], v[2:5]
	s_nop 2
	ds_read_b64_tr_b16 v[2:3], v103
	ds_read_b64_tr_b16 v[4:5], v103 offset:1088
	ds_read_b64_tr_b16 v[64:65], v40 offset:34816
	ds_read_b64_tr_b16 v[66:67], v40 offset:36928
	ds_read_b64_tr_b16 v[82:83], v40 offset:37056
	ds_read_b64_tr_b16 v[80:81], v40 offset:34944
	ds_read_b64_tr_b16 v[84:85], v103 offset:128
	ds_read_b64_tr_b16 v[88:89], v103 offset:256
	ds_read_b64_tr_b16 v[92:93], v103 offset:384
	ds_read_b64_tr_b16 v[86:87], v103 offset:1216
	ds_read_b64_tr_b16 v[90:91], v103 offset:1344
	ds_read_b64_tr_b16 v[94:95], v103 offset:1472
	v_add_u32_e32 v40, s30, v172
	v_mad_i64_i32 v[40:41], s[50:51], v40, s33, v[42:43]
	s_waitcnt lgkmcnt(8)
	v_mfma_f32_16x16x32_bf16 v[32:35], v[2:5], v[64:67], v[32:35]
	v_lshl_add_u64 v[40:41], v[40:41], 0, s[62:63]
	v_lshl_add_u64 v[40:41], v[40:41], 0, s[36:37]
	v_lshl_add_u64 v[40:41], v[40:41], 0, v[14:15]
	s_waitcnt lgkmcnt(6)
	v_mfma_f32_16x16x32_bf16 v[96:99], v[2:5], v[80:83], v[6:9]
	v_add_u32_e32 v2, s30, v1
	v_mad_i64_i32 v[2:3], s[50:51], v2, s33, v[42:43]
	v_lshl_add_u64 v[2:3], v[2:3], 0, s[62:63]
	v_lshl_add_u64 v[2:3], v[2:3], 0, s[36:37]
	v_lshl_add_u64 v[6:7], v[2:3], 0, v[14:15]
	ds_read_b64_tr_b16 v[2:3], v103 offset:512
	ds_read_b64_tr_b16 v[4:5], v103 offset:1600
	s_waitcnt lgkmcnt(4)
	v_mfma_f32_16x16x32_bf16 v[36:39], v[84:87], v[64:67], v[36:39]
	v_add_u32_e32 v8, s30, v147
	v_mad_i64_i32 v[8:9], s[50:51], v8, s33, v[42:43]
	v_mfma_f32_16x16x32_bf16 v[20:23], v[84:87], v[80:83], v[20:23]
	v_add_co_u32_e32 v6, vcc, s49, v6
	s_waitcnt lgkmcnt(3)
	v_mfma_f32_16x16x32_bf16 v[44:47], v[88:91], v[64:67], v[44:47]
	v_addc_co_u32_e32 v7, vcc, 0, v7, vcc
	v_mfma_f32_16x16x32_bf16 v[24:27], v[88:91], v[80:83], v[24:27]
	s_waitcnt lgkmcnt(2)
	v_mfma_f32_16x16x32_bf16 v[48:51], v[92:95], v[64:67], v[48:51]
	v_mfma_f32_16x16x32_bf16 v[28:31], v[92:95], v[80:83], v[28:31]
	ds_read_b64_tr_b16 v[84:85], v103 offset:640
	ds_read_b64_tr_b16 v[88:89], v103 offset:768
	ds_read_b64_tr_b16 v[92:93], v103 offset:896
	ds_read_b64_tr_b16 v[86:87], v103 offset:1728
	ds_read_b64_tr_b16 v[90:91], v103 offset:1856
	ds_read_b64_tr_b16 v[94:95], v103 offset:1984
	s_waitcnt lgkmcnt(6)
	v_mfma_f32_16x16x32_bf16 v[68:71], v[2:5], v[64:67], v[68:71]
	v_mfma_f32_16x16x32_bf16 v[52:55], v[2:5], v[80:83], v[52:55]
	v_lshl_add_u64 v[2:3], v[8:9], 0, s[62:63]
	v_lshl_add_u64 v[2:3], v[2:3], 0, s[36:37]
	v_lshl_add_u64 v[2:3], v[2:3], 0, v[14:15]
	s_waitcnt lgkmcnt(2)
	v_mfma_f32_16x16x32_bf16 v[72:75], v[84:87], v[64:67], v[72:75]
	v_add_co_u32_e32 v8, vcc, s49, v2
	s_waitcnt lgkmcnt(1)
	v_mfma_f32_16x16x32_bf16 v[76:79], v[88:91], v[64:67], v[76:79]
	v_addc_co_u32_e32 v9, vcc, 0, v3, vcc
	v_add_co_u32_e32 v40, vcc, s49, v40
	s_waitcnt lgkmcnt(0)
; #define LAS __attribute__((address_space(3)))
; __device__ __forceinline__ s16x4 tr16(const LAS unsigned char* p) { return __builtin_bit_cast(s16x4, __builtin_amdgcn_ds_read_tr16_b64_v4i16((LAS s16x4*)p)); }
; __device__ __forceinline__ bf16x8 cat8(s16x4 lo, s16x4 hi) { return __builtin_shufflevector(lo, hi, 0, 1, 2, 3, 4, 5, 6, 7); }
; __device__ __forceinline__ f32x4 mfma16(bf16x8 a, bf16x8 b, f32x4 c) { return __builtin_amdgcn_mfma_f32_16x16x32_bf16(a, b, c, 0, 0, 0); }
; __device__ __forceinline__ void ret_scan(const bf16* proj, bf16* ST, bf16* FS, const float* dexp, LAS unsigned char* lds, int vb, int nb, int tid_in, int wave) {
;     ...
;             if (step + 1 < nsteps) { const int n1 = dir == 0 ? step + 1 : N - 2 - step, rowb = base + n1 * 128;
; #pragma unroll
;                 for (int i = 0; i < 4; ++i) { const int id = tid + 512 * i, j = id >> 4, ch = id & 15; kr[i] = *(const v4u*)(proj + (size_t)(rowb + j) * NIN + C_RK + h * 256 + dsl * 128 + ch * 8); }
; #pragma unroll
;                 for (int i = 0; i < 8; ++i) { const int id = tid + 512 * i, j = id >> 5, ch = id & 31; vr[i] = *(const v4u*)(proj + (size_t)(rowb + j) * NIN + C_RV + h * 256 + ch * 8); } }
; #pragma unroll
;             for (int m = 0; m < 8; ++m) { acc[m][0] = acc[m][0] * gC; acc[m][1] = acc[m][1] * gC; }
; #pragma unroll
;             for (int ks = 0; ks < 4; ++ks) {
;                 const int rho = 8 * ks + 2 * g, lo8 = (qi >> 2) * 32 + (qi & 3) * 8;
;                 bf16x8 bfr[2];
; #pragma unroll
;                 for (int nt = 0; nt < 2; ++nt) { const LAS unsigned char* p = Vt + rho * 2112 + (2 * wave + nt) * 128 + lo8; bfr[nt] = cat8(tr16(p), tr16(p + 2112)); }
; #pragma unroll
;                 for (int m = 0; m < 8; ++m) { const LAS unsigned char* p = Kt + rho * 1088 + m * 128 + lo8; const bf16x8 af = cat8(tr16(p), tr16(p + 1088));
;                     acc[m][0] = mfma16(af, bfr[0], acc[m][0]); acc[m][1] = mfma16(af, bfr[1], acc[m][1]); }
	v_mfma_f32_16x16x32_bf16 v[64:67], v[92:95], v[64:67], v[10:13]
	global_load_dwordx4 v[2:5], v[6:7], off
	s_nop 0
	global_load_dwordx4 v[6:9], v[8:9], off
	v_add_u32_e32 v10, s30, v173
	v_mad_i64_i32 v[100:101], s[50:51], v10, s33, v[42:43]
	v_mfma_f32_16x16x32_bf16 v[56:59], v[84:87], v[80:83], v[56:59]
	v_mov_b32_e32 v10, 0x4200
	v_mad_u32_u24 v10, v111, s73, v10
	v_addc_co_u32_e32 v41, vcc, 0, v41, vcc
	v_mfma_f32_16x16x32_bf16 v[60:63], v[88:91], v[80:83], v[60:63]
	v_add_u32_e32 v205, v115, v10
	v_mfma_f32_16x16x32_bf16 v[80:83], v[92:95], v[80:83], v[16:19]
	ds_read_b64_tr_b16 v[10:11], v103 offset:8704
	ds_read_b64_tr_b16 v[12:13], v103 offset:9792
	ds_read_b64_tr_b16 v[84:85], v205 offset:34816
	ds_read_b64_tr_b16 v[86:87], v205 offset:36928
	ds_read_b64_tr_b16 v[90:91], v205 offset:37056
	ds_read_b64_tr_b16 v[88:89], v205 offset:34944
	ds_read_b64_tr_b16 v[92:93], v103 offset:8832
	ds_read_b64_tr_b16 v[104:105], v103 offset:8960
	ds_read_b64_tr_b16 v[118:119], v103 offset:9088
	ds_read_b64_tr_b16 v[94:95], v103 offset:9920
	ds_read_b64_tr_b16 v[106:107], v103 offset:10048
	ds_read_b64_tr_b16 v[120:121], v103 offset:10176
	v_lshl_add_u64 v[16:17], v[100:101], 0, s[62:63]
	v_lshl_add_u64 v[16:17], v[16:17], 0, s[36:37]
	v_add_u32_e32 v18, s30, v174
	v_lshl_add_u64 v[14:15], v[16:17], 0, v[14:15]
	v_mad_i64_i32 v[18:19], s[36:37], v18, s33, v[42:43]
	v_add_co_u32_e32 v14, vcc, s49, v14
	v_lshl_add_u64 v[18:19], v[18:19], 0, s[62:63]
	s_nop 0
	v_addc_co_u32_e32 v15, vcc, 0, v15, vcc
	v_lshl_add_u64 v[18:19], v[18:19], 0, v[182:183]
	s_waitcnt lgkmcnt(8)
	v_mfma_f32_16x16x32_bf16 v[122:125], v[10:13], v[84:87], v[32:35]
	s_waitcnt lgkmcnt(6)
	v_mfma_f32_16x16x32_bf16 v[96:99], v[10:13], v[88:91], v[96:99]
	global_load_dwordx4 v[10:13], v[40:41], off
	s_nop 0
	global_load_dwordx4 v[14:17], v[14:15], off
	s_waitcnt lgkmcnt(2)
	v_mfma_f32_16x16x32_bf16 v[34:37], v[92:95], v[84:87], v[36:39]
	v_mfma_f32_16x16x32_bf16 v[38:41], v[92:95], v[88:91], v[20:23]
	s_nop 2
	v_add_co_u32_e32 v22, vcc, s40, v18
	v_add_u32_e32 v18, s30, v175
	s_nop 0
	v_addc_co_u32_e32 v23, vcc, 0, v19, vcc
	v_mad_i64_i32 v[18:19], s[36:37], v18, s33, v[42:43]
	s_waitcnt lgkmcnt(1)
	v_mfma_f32_16x16x32_bf16 v[92:95], v[104:107], v[88:91], v[24:27]
	s_nop 2
	v_lshl_add_u64 v[24:25], v[18:19], 0, s[62:63]
	ds_read_b64_tr_b16 v[18:19], v103 offset:9216
	ds_read_b64_tr_b16 v[20:21], v103 offset:10304
	v_mfma_f32_16x16x32_bf16 v[44:47], v[104:107], v[84:87], v[44:47]
	v_lshl_add_u64 v[24:25], v[24:25], 0, v[182:183]
	v_add_co_u32_e32 v24, vcc, s40, v24
	s_waitcnt lgkmcnt(2)
	v_mfma_f32_16x16x32_bf16 v[104:107], v[118:121], v[84:87], v[48:51]
	v_addc_co_u32_e32 v25, vcc, 0, v25, vcc
	v_mfma_f32_16x16x32_bf16 v[118:121], v[118:121], v[88:91], v[28:31]
	ds_read_b64_tr_b16 v[26:27], v103 offset:9344
	s_nop 1
	ds_read_b64_tr_b16 v[30:31], v103 offset:9472
	ds_read_b64_tr_b16 v[48:49], v103 offset:9600
	ds_read_b64_tr_b16 v[28:29], v103 offset:10432
	ds_read_b64_tr_b16 v[32:33], v103 offset:10560
	ds_read_b64_tr_b16 v[50:51], v103 offset:10688
	s_waitcnt lgkmcnt(6)
	v_mfma_f32_16x16x32_bf16 v[130:133], v[18:21], v[88:91], v[52:55]
	s_nop 2
	v_add_u32_e32 v52, s30, v176
	v_mad_i64_i32 v[52:53], s[36:37], v52, s33, v[42:43]
	s_waitcnt lgkmcnt(2)
	v_mfma_f32_16x16x32_bf16 v[134:137], v[26:29], v[84:87], v[72:75]
	v_lshl_add_u64 v[52:53], v[52:53], 0, s[62:63]
	v_lshl_add_u64 v[52:53], v[52:53], 0, v[182:183]
	v_mfma_f32_16x16x32_bf16 v[138:141], v[26:29], v[88:91], v[56:59]
	v_add_u32_e32 v28, s30, v177
	v_mad_i64_i32 v[28:29], s[36:37], v28, s33, v[42:43]
	v_add_co_u32_e32 v26, vcc, s40, v52
	v_lshl_add_u64 v[28:29], v[28:29], 0, s[62:63]
	s_nop 0
	v_addc_co_u32_e32 v27, vcc, 0, v53, vcc
	v_lshl_add_u64 v[28:29], v[28:29], 0, v[182:183]
	s_waitcnt lgkmcnt(1)
	v_mfma_f32_16x16x32_bf16 v[142:145], v[30:33], v[84:87], v[76:79]
	v_add_u32_e32 v58, s30, v178
	v_mfma_f32_16x16x32_bf16 v[160:163], v[30:33], v[88:91], v[60:63]
	v_add_co_u32_e32 v30, vcc, s40, v28
	s_nop 1
	v_addc_co_u32_e32 v31, vcc, 0, v29, vcc
	v_mfma_f32_16x16x32_bf16 v[126:129], v[18:21], v[84:87], v[68:71]
	global_load_dwordx4 v[18:21], v[22:23], off
	s_nop 0
	global_load_dwordx4 v[22:25], v[24:25], off
	s_nop 0
	global_load_dwordx4 v[26:29], v[26:27], off
	s_nop 0
	global_load_dwordx4 v[30:33], v[30:31], off
	s_waitcnt lgkmcnt(0)
	v_mfma_f32_16x16x32_bf16 v[164:167], v[48:51], v[84:87], v[64:67]
	v_mfma_f32_16x16x32_bf16 v[168:171], v[48:51], v[88:91], v[80:83]
	ds_read_b64_tr_b16 v[54:55], v103 offset:17408
	ds_read_b64_tr_b16 v[56:57], v103 offset:18496
	ds_read_b64_tr_b16 v[206:207], v205 offset:51712
	ds_read_b64_tr_b16 v[208:209], v205 offset:53824
	ds_read_b64_tr_b16 v[228:229], v205 offset:53952
	ds_read_b64_tr_b16 v[226:227], v205 offset:51840
	ds_read_b64_tr_b16 v[62:63], v103 offset:17536
	ds_read_b64_tr_b16 v[70:71], v103 offset:17664
	ds_read_b64_tr_b16 v[78:79], v103 offset:17792
	ds_read_b64_tr_b16 v[64:65], v103 offset:18624
	ds_read_b64_tr_b16 v[72:73], v103 offset:18752
	ds_read_b64_tr_b16 v[80:81], v103 offset:18880
	v_mad_i64_i32 v[48:49], s[36:37], v58, s33, v[42:43]
	v_lshl_add_u64 v[48:49], v[48:49], 0, s[62:63]
	v_add_u32_e32 v66, s30, v179
	v_lshl_add_u64 v[48:49], v[48:49], 0, v[182:183]
	s_waitcnt lgkmcnt(2)
; #define LAS __attribute__((address_space(3)))
; __device__ __forceinline__ unsigned pk2(float lo, float hi) { const f32x2 v = {lo, hi}; return __builtin_bit_cast(unsigned, __builtin_convertvector(v, bf16x2_t)); }
; __device__ __forceinline__ s16x4 tr16(const LAS unsigned char* p) { return __builtin_bit_cast(s16x4, __builtin_amdgcn_ds_read_tr16_b64_v4i16((LAS s16x4*)p)); }
; __device__ __forceinline__ bf16x8 cat8(s16x4 lo, s16x4 hi) { return __builtin_shufflevector(lo, hi, 0, 1, 2, 3, 4, 5, 6, 7); }
; __device__ __forceinline__ f32x4 mfma16(bf16x8 a, bf16x8 b, f32x4 c) { return __builtin_amdgcn_mfma_f32_16x16x32_bf16(a, b, c, 0, 0, 0); }
; __device__ __forceinline__ void ret_scan(const bf16* proj, bf16* ST, bf16* FS, const float* dexp, LAS unsigned char* lds, int vb, int nb, int tid_in, int wave) {
;     ...
;             for (int m = 0; m < 8; ++m) { acc[m][0] = acc[m][0] * gC; acc[m][1] = acc[m][1] * gC; }
; #pragma unroll
;             for (int ks = 0; ks < 4; ++ks) {
;                 const int rho = 8 * ks + 2 * g, lo8 = (qi >> 2) * 32 + (qi & 3) * 8;
;                 bf16x8 bfr[2];
; #pragma unroll
;                 for (int nt = 0; nt < 2; ++nt) { const LAS unsigned char* p = Vt + rho * 2112 + (2 * wave + nt) * 128 + lo8; bfr[nt] = cat8(tr16(p), tr16(p + 2112)); }
; #pragma unroll
;                 for (int m = 0; m < 8; ++m) { const LAS unsigned char* p = Kt + rho * 1088 + m * 128 + lo8; const bf16x8 af = cat8(tr16(p), tr16(p + 1088));
;                     acc[m][0] = mfma16(af, bfr[0], acc[m][0]); acc[m][1] = mfma16(af, bfr[1], acc[m][1]); }
;             }
;             dst_prev = step < 15 ? ST + ((size_t)(((base >> 7) + tgt) * 8 + h) * 2 + dir) * 65536 : FS + ((size_t)((vs - 8) * 8 + h) * 2 + dir) * 65536;
; #pragma unroll
;             for (int m = 0; m < 8; ++m)
; #pragma unroll
;                 for (int nt = 0; nt < 2; ++nt) { stq[m][nt].x = pk2(acc[m][nt].x, acc[m][nt].y); stq[m][nt].y = pk2(acc[m][nt].z, acc[m][nt].w); }
	v_mfma_f32_16x16x32_bf16 v[58:61], v[62:65], v[206:209], v[34:37]
	v_add_co_u32_e32 v48, vcc, s40, v48
	v_add_u32_e32 v90, s30, v181
	s_nop 0
	v_mad_i64_i32 v[34:35], s[36:37], v66, s33, v[42:43]
	v_lshl_add_u64 v[34:35], v[34:35], 0, s[62:63]
	v_addc_co_u32_e32 v49, vcc, 0, v49, vcc
	v_lshl_add_u64 v[34:35], v[34:35], 0, v[182:183]
	v_mfma_f32_16x16x32_bf16 v[62:65], v[62:65], v[226:229], v[38:41]
	s_nop 2
	v_add_co_u32_e32 v38, vcc, s40, v34
	s_waitcnt lgkmcnt(1)
	v_mfma_f32_16x16x32_bf16 v[66:69], v[70:73], v[206:209], v[44:47]
	v_addc_co_u32_e32 v39, vcc, 0, v35, vcc
	global_load_dwordx4 v[34:37], v[48:49], off
	s_nop 0
	global_load_dwordx4 v[38:41], v[38:39], off
	v_add_u32_e32 v44, s30, v180
	v_mad_i64_i32 v[44:45], s[36:37], v44, s33, v[42:43]
	v_lshl_add_u64 v[48:49], v[44:45], 0, s[62:63]
	ds_read_b64_tr_b16 v[44:45], v103 offset:17920
	ds_read_b64_tr_b16 v[46:47], v103 offset:19008
	v_lshl_add_u64 v[48:49], v[48:49], 0, v[182:183]
	v_mad_i64_i32 v[42:43], s[30:31], v90, s33, v[42:43]
	v_add_co_u32_e32 v48, vcc, s40, v48
	v_lshl_add_u64 v[42:43], v[42:43], 0, s[62:63]
	s_nop 0
	v_addc_co_u32_e32 v49, vcc, 0, v49, vcc
	v_lshl_add_u64 v[42:43], v[42:43], 0, v[182:183]
	s_waitcnt lgkmcnt(0)
	v_mfma_f32_16x16x32_bf16 v[82:85], v[44:47], v[206:209], v[126:129]
	s_and_b32 s30, s42, 15
	s_add_i32 s30, s56, s30
	s_lshl_b32 s30, s30, 3
	v_mfma_f32_16x16x32_bf16 v[86:89], v[44:47], v[226:229], v[130:133]
	v_add_co_u32_e32 v46, vcc, s40, v42
	v_lshl_or_b32 v182, v110, 2, s64
	s_nop 0
	v_addc_co_u32_e32 v47, vcc, 0, v43, vcc
	v_mfma_f32_16x16x32_bf16 v[50:53], v[54:57], v[206:209], v[122:125]
	s_or_b32 s30, s30, s47
	s_ashr_i32 s31, s30, 31
	s_lshl_b64 s[30:31], s[30:31], 18
	v_mfma_f32_16x16x32_bf16 v[54:57], v[54:57], v[226:229], v[96:99]
	s_add_u32 s50, s57, s30
	s_addc_u32 s51, s58, s31
	v_cvt_pk_bf16_f32 v122, v58, v59
	v_mfma_f32_16x16x32_bf16 v[70:73], v[70:73], v[226:229], v[92:95]
	v_cvt_pk_bf16_f32 v123, v60, v61
	v_cvt_pk_bf16_f32 v124, v62, v63
	v_cvt_pk_bf16_f32 v125, v64, v65
	v_mfma_f32_16x16x32_bf16 v[74:77], v[78:81], v[206:209], v[104:107]
	v_cvt_pk_bf16_f32 v126, v66, v67
	v_cvt_pk_bf16_f32 v127, v68, v69
	s_nop 1
	v_cvt_pk_bf16_f32 v128, v70, v71
	v_mfma_f32_16x16x32_bf16 v[78:81], v[78:81], v[226:229], v[118:121]
	ds_read_b64_tr_b16 v[94:95], v103 offset:18048
	ds_read_b64_tr_b16 v[104:105], v103 offset:18176
	s_nop 0
	ds_read_b64_tr_b16 v[118:119], v103 offset:18304
	ds_read_b64_tr_b16 v[96:97], v103 offset:19136
	ds_read_b64_tr_b16 v[106:107], v103 offset:19264
	ds_read_b64_tr_b16 v[120:121], v103 offset:19392
	global_load_dwordx4 v[42:45], v[48:49], off
	s_nop 0
	global_load_dwordx4 v[46:49], v[46:47], off
	v_cvt_pk_bf16_f32 v129, v72, v73
	s_waitcnt lgkmcnt(2)
	v_mfma_f32_16x16x32_bf16 v[90:93], v[94:97], v[206:209], v[134:137]
	v_cvt_pk_bf16_f32 v130, v74, v75
	v_cvt_pk_bf16_f32 v131, v76, v77
	v_cvt_pk_bf16_f32 v132, v78, v79
	v_mfma_f32_16x16x32_bf16 v[94:97], v[94:97], v[226:229], v[138:141]
	v_cvt_pk_bf16_f32 v133, v80, v81
	v_cvt_pk_bf16_f32 v134, v82, v83
	v_cvt_pk_bf16_f32 v135, v84, v85
	s_waitcnt lgkmcnt(1)
	v_mfma_f32_16x16x32_bf16 v[98:101], v[104:107], v[206:209], v[142:145]
	v_cvt_pk_bf16_f32 v136, v86, v87
	v_cvt_pk_bf16_f32 v137, v88, v89
	v_cvt_pk_bf16_f32 v138, v90, v91
	v_mfma_f32_16x16x32_bf16 v[102:105], v[104:107], v[226:229], v[160:163]
	v_cvt_pk_bf16_f32 v139, v92, v93
	v_cvt_pk_bf16_f32 v140, v94, v95
	v_cvt_pk_bf16_f32 v141, v96, v97
	s_waitcnt lgkmcnt(0)
	v_mfma_f32_16x16x32_bf16 v[106:109], v[118:121], v[206:209], v[164:167]
	v_mul_u32_u24_e32 v209, 0x440, v111
	v_lshl_or_b32 v160, v149, 8, s45
	v_or_b32_e32 v162, 0x1000, v160
	v_mul_u32_u24_e32 v165, 0x880, v110
	v_mul_u32_u24_e32 v167, 0x840, v111
	v_mfma_f32_16x16x32_bf16 v[110:113], v[118:121], v[226:229], v[168:171]
	v_cvt_pk_bf16_f32 v118, v50, v51
	v_cvt_pk_bf16_f32 v119, v52, v53
	v_cvt_pk_bf16_f32 v120, v54, v55
	v_cvt_pk_bf16_f32 v121, v56, v57
	v_cvt_pk_bf16_f32 v142, v98, v99
	v_cvt_pk_bf16_f32 v143, v100, v101
	v_cvt_pk_bf16_f32 v144, v102, v103
	v_cvt_pk_bf16_f32 v145, v104, v105
	v_cvt_pk_bf16_f32 v168, v106, v107
	v_cvt_pk_bf16_f32 v169, v108, v109
	v_cvt_pk_bf16_f32 v170, v110, v111
	v_cvt_pk_bf16_f32 v171, v112, v113
	v_ashrrev_i32_e32 v161, 31, v160
	v_ashrrev_i32_e32 v163, 31, v162
	v_lshlrev_b32_e32 v182, 1, v182
	s_lshl_b32 s62, s43, 1
	s_lshl_b32 s36, s64, 1
	v_and_b32_e32 v164, 15, v248
	v_lshlrev_b32_e32 v164, 4, v164
	v_lshlrev_b32_e32 v166, 1, v116
	v_add_u32_e32 v206, v115, v210
	v_add_u32_e32 v207, v117, v165
	v_add_u32_e32 v208, v115, v167
	v_add_u32_e32 v209, v117, v209
	s_branch .LBB0_416
